# k26: k24 + residual epilogues: second-half residual rows touched with throw-away loads during the first-half fetch (6 phases); one phase's two serialized single loads issued together
# baseline (speedup 1.0000x reference)
.LBB0_587:
	s_lshl_b32 s13, s13, 8
	v_lshl_or_b32 v170, s12, 8, v184
	v_add_u32_e32 v174, s13, v182
	v_ashrrev_i32_e32 v171, 31, v170
	v_lshlrev_b64 v[200:201], 1, v[170:171]
	v_ashrrev_i32_e32 v175, 31, v174
	v_lshl_add_u64 v[172:173], s[78:79], 0, v[200:201]
	v_lshlrev_b64 v[202:203], 11, v[174:175]
	v_lshl_add_u64 v[130:131], v[172:173], 0, v[202:203]
	global_load_dwordx4 v[192:195], v[130:131], off
	global_load_dwordx4 v[196:199], v[130:131], off offset:256
	v_or_b32_e32 v130, 16, v174
	v_or_b32_e32 v132, 32, v174
	v_or_b32_e32 v134, 48, v174
	v_ashrrev_i32_e32 v131, 31, v130
	v_ashrrev_i32_e32 v133, 31, v132
	v_ashrrev_i32_e32 v135, 31, v134
	v_lshlrev_b64 v[180:181], 11, v[130:131]
	v_lshlrev_b64 v[178:179], 11, v[132:133]
	v_lshlrev_b64 v[176:177], 11, v[134:135]
	v_lshl_add_u64 v[130:131], v[172:173], 0, v[180:181]
	v_lshl_add_u64 v[132:133], v[172:173], 0, v[178:179]
	v_lshl_add_u64 v[204:205], v[172:173], 0, v[176:177]
	v_add_co_u32_e32 v250, vcc, 0x38000, v130
	s_nop 1
	v_addc_co_u32_e32 v251, vcc, 0, v131, vcc
	global_load_dwordx4 v[246:249], v[250:251], off
	global_load_dwordx4 v[246:249], v[250:251], off offset:256
	v_add_co_u32_e32 v250, vcc, 0x40000, v130
	s_nop 1
	v_addc_co_u32_e32 v251, vcc, 0, v131, vcc
	global_load_dwordx4 v[246:249], v[250:251], off
	global_load_dwordx4 v[246:249], v[250:251], off offset:256
	v_add_co_u32_e32 v250, vcc, 0x40000, v132
	s_nop 1
	v_addc_co_u32_e32 v251, vcc, 0, v133, vcc
	global_load_dwordx4 v[246:249], v[250:251], off
	global_load_dwordx4 v[246:249], v[250:251], off offset:256
	v_add_co_u32_e32 v250, vcc, 0x40000, v204
	s_nop 1
	v_addc_co_u32_e32 v251, vcc, 0, v205, vcc
	global_load_dwordx4 v[246:249], v[250:251], off
	global_load_dwordx4 v[246:249], v[250:251], off offset:256
	global_load_dwordx4 v[150:153], v[130:131], off
	global_load_dwordx4 v[146:149], v[130:131], off offset:256
	global_load_dwordx4 v[142:145], v[132:133], off
	global_load_dwordx4 v[138:141], v[132:133], off offset:256
	global_load_dwordx4 v[134:137], v[204:205], off
	s_nop 0
	global_load_dwordx4 v[130:133], v[204:205], off offset:256
	v_and_b32_e32 v204, 64, v190
	v_xor_b32_e32 v191, 16, v190
	v_add_u32_e32 v204, 64, v204
	v_xor_b32_e32 v205, 32, v190
	v_cmp_lt_i32_e32 vcc, v191, v204
	v_lshl_add_u64 v[202:203], s[78:79], 0, v[202:203]
	v_lshl_add_u64 v[200:201], v[202:203], 0, v[200:201]
	v_cndmask_b32_e32 v191, v190, v191, vcc
	v_cmp_lt_i32_e32 vcc, v205, v204
	v_lshlrev_b32_e32 v191, 2, v191
	s_waitcnt vmcnt(0)
	v_lshlrev_b32_e32 v204, 16, v194
	v_cndmask_b32_e32 v210, v190, v205, vcc
	v_and_b32_e32 v205, 0xffff0000, v194
	v_lshlrev_b32_e32 v194, 16, v195
	v_and_b32_e32 v195, 0xffff0000, v195
	v_lshlrev_b32_e32 v202, 16, v192
	v_and_b32_e32 v203, 0xffff0000, v192
	v_lshlrev_b32_e32 v192, 16, v193
	v_and_b32_e32 v193, 0xffff0000, v193
	v_lshlrev_b32_e32 v206, 16, v196
	v_and_b32_e32 v207, 0xffff0000, v196
	v_lshlrev_b32_e32 v196, 16, v197
	v_and_b32_e32 v197, 0xffff0000, v197
	v_lshlrev_b32_e32 v208, 16, v198
	v_and_b32_e32 v209, 0xffff0000, v198
	v_lshlrev_b32_e32 v198, 16, v199
	v_and_b32_e32 v199, 0xffff0000, v199
	v_pk_add_f32 v[124:125], v[124:125], v[194:195]
	v_pk_add_f32 v[122:123], v[122:123], v[204:205]
	v_pk_add_f32 v[126:127], v[126:127], v[202:203]
	v_pk_add_f32 v[128:129], v[128:129], v[192:193]
	v_pk_add_f32 v[120:121], v[120:121], v[196:197]
	v_pk_add_f32 v[194:195], v[116:117], v[198:199]
	v_pk_mul_f32 v[116:117], v[122:123], v[122:123]
	v_pk_mul_f32 v[196:197], v[124:125], v[124:125]
	v_pk_add_f32 v[118:119], v[118:119], v[206:207]
	v_pk_add_f32 v[192:193], v[114:115], v[208:209]
	v_cvt_pk_bf16_f32 v114, v126, v127
	v_cvt_pk_bf16_f32 v115, v128, v129
	v_pk_fma_f32 v[128:129], v[128:129], v[128:129], v[196:197]
	v_pk_fma_f32 v[116:117], v[126:127], v[126:127], v[116:117]
	v_pk_fma_f32 v[126:127], v[120:121], v[120:121], v[128:129]
	v_pk_fma_f32 v[116:117], v[118:119], v[118:119], v[116:117]
	v_pk_fma_f32 v[126:127], v[194:195], v[194:195], v[126:127]
	v_pk_fma_f32 v[116:117], v[192:193], v[192:193], v[116:117]
	s_nop 0
	v_add_f32_e32 v116, v116, v117
	v_add_f32_e32 v117, v126, v127
	v_add_f32_e32 v126, v116, v117
	ds_bpermute_b32 v127, v191, v126
	v_cvt_pk_bf16_f32 v116, v122, v123
	v_cvt_pk_bf16_f32 v117, v124, v125
	global_store_dwordx4 v[200:201], v[114:117], off
	v_cvt_pk_bf16_f32 v118, v118, v119
	v_cvt_pk_bf16_f32 v119, v120, v121
	v_cvt_pk_bf16_f32 v120, v192, v193
	v_cvt_pk_bf16_f32 v121, v194, v195
	global_store_dwordx4 v[200:201], v[118:121], off offset:256
	s_waitcnt lgkmcnt(0)
	v_add_f32_e32 v115, v126, v127
	v_lshlrev_b32_e32 v114, 2, v210
	ds_bpermute_b32 v116, v114, v115
	s_and_saveexec_b64 s[2:3], s[4:5]
	s_cbranch_execz .LBB0_589
	s_waitcnt lgkmcnt(0)
	v_add_f32_e32 v115, v115, v116
	ds_write_b32 v185, v115

.LBB0_595:
	s_or_b64 exec, exec, s[2:3]
	v_lshlrev_b64 v[70:71], 11, v[174:175]
	s_mov_b64 s[0:1], 0x40000
	v_lshl_add_u64 v[104:105], v[70:71], 0, s[0:1]
	v_lshl_add_u64 v[72:73], v[172:173], 0, v[104:105]
	s_waitcnt lgkmcnt(0)
	global_load_dwordx4 v[66:69], v[72:73], off
	global_load_dwordx4 v[116:119], v[72:73], off offset:256
	s_mov_b64 s[0:1], 0x48000
	v_lshl_add_u64 v[94:95], v[70:71], 0, s[0:1]
	s_mov_b64 s[0:1], 0x50000
	v_lshl_add_u64 v[92:93], v[70:71], 0, s[0:1]
	s_mov_b64 s[0:1], 0x58000
	v_lshl_add_u64 v[90:91], v[70:71], 0, s[0:1]
	s_waitcnt vmcnt(1)
	v_lshlrev_b32_e32 v106, 16, v66
	v_and_b32_e32 v107, 0xffff0000, v66
	v_lshlrev_b32_e32 v108, 16, v67
	v_and_b32_e32 v109, 0xffff0000, v67
	v_lshlrev_b32_e32 v110, 16, v68
	v_and_b32_e32 v111, 0xffff0000, v68
	v_lshlrev_b32_e32 v112, 16, v69
	v_and_b32_e32 v113, 0xffff0000, v69
	v_pk_add_f32 v[62:63], v[62:63], v[106:107]
	v_pk_add_f32 v[106:107], v[60:61], v[112:113]
	v_pk_add_f32 v[60:61], v[58:59], v[110:111]
	v_pk_add_f32 v[64:65], v[64:65], v[108:109]
	v_pk_mul_f32 v[58:59], v[60:61], v[60:61]
	v_pk_mul_f32 v[108:109], v[106:107], v[106:107]
	v_pk_fma_f32 v[110:111], v[62:63], v[62:63], v[58:59]
	v_lshl_add_u64 v[58:59], s[78:79], 0, v[104:105]
	v_pk_fma_f32 v[108:109], v[64:65], v[64:65], v[108:109]
	v_lshl_add_u64 v[104:105], v[170:171], 1, v[58:59]
	s_waitcnt vmcnt(0)
	v_lshlrev_b32_e32 v98, 16, v116
	v_and_b32_e32 v99, 0xffff0000, v116
	v_lshlrev_b32_e32 v102, 16, v117
	v_and_b32_e32 v103, 0xffff0000, v117
	v_lshl_add_u64 v[66:67], v[172:173], 0, v[94:95]
	global_load_dwordx4 v[86:89], v[66:67], off
	global_load_dwordx4 v[82:85], v[66:67], off offset:256
	v_lshl_add_u64 v[66:67], v[172:173], 0, v[92:93]
	global_load_dwordx4 v[78:81], v[66:67], off
	global_load_dwordx4 v[74:77], v[66:67], off offset:256
	v_lshl_add_u64 v[66:67], v[172:173], 0, v[90:91]
	v_lshlrev_b32_e32 v100, 16, v118
	v_and_b32_e32 v101, 0xffff0000, v118
	v_lshlrev_b32_e32 v96, 16, v119
	v_and_b32_e32 v97, 0xffff0000, v119
	global_load_dwordx4 v[70:73], v[66:67], off
	s_nop 0
	global_load_dwordx4 v[66:69], v[66:67], off offset:256
	v_cvt_pk_bf16_f32 v58, v62, v63
	v_cvt_pk_bf16_f32 v59, v64, v65
	v_cvt_pk_bf16_f32 v60, v60, v61
	v_cvt_pk_bf16_f32 v61, v106, v107
	v_pk_add_f32 v[56:57], v[56:57], v[102:103]
	v_pk_add_f32 v[54:55], v[54:55], v[98:99]
	global_store_dwordx4 v[104:105], v[58:61], off
	s_nop 1
	v_pk_add_f32 v[58:59], v[50:51], v[100:101]
	v_pk_add_f32 v[60:61], v[52:53], v[96:97]
	v_pk_fma_f32 v[50:51], v[54:55], v[54:55], v[110:111]
	v_pk_fma_f32 v[52:53], v[56:57], v[56:57], v[108:109]
	v_pk_fma_f32 v[64:65], v[58:59], v[58:59], v[50:51]
	v_pk_fma_f32 v[62:63], v[60:61], v[60:61], v[52:53]
	v_cvt_pk_bf16_f32 v50, v54, v55
	v_cvt_pk_bf16_f32 v51, v56, v57
	v_cvt_pk_bf16_f32 v52, v58, v59
	v_cvt_pk_bf16_f32 v53, v60, v61
	global_store_dwordx4 v[104:105], v[50:53], off offset:256
	s_nop 1
	v_add_f32_e32 v50, v64, v65
	v_add_f32_e32 v51, v62, v63
	v_add_f32_e32 v50, v50, v51
	ds_bpermute_b32 v51, v191, v50
	s_waitcnt lgkmcnt(0)
	v_add_f32_e32 v50, v50, v51
	ds_bpermute_b32 v51, v114, v50
	s_and_saveexec_b64 s[2:3], s[4:5]
	s_cbranch_execz .LBB0_597
	s_waitcnt lgkmcnt(0)
	v_add_f32_e32 v50, v50, v51
	ds_write_b32 v185, v50 offset:512

.LBB0_923:
	s_lshl_b32 s11, s26, 8
	v_lshl_or_b32 v170, s10, 8, v184
	v_add_u32_e32 v174, s11, v182
	v_ashrrev_i32_e32 v171, 31, v170
	v_lshlrev_b64 v[200:201], 1, v[170:171]
	v_ashrrev_i32_e32 v175, 31, v174
	v_lshl_add_u64 v[172:173], s[78:79], 0, v[200:201]
	v_lshlrev_b64 v[202:203], 11, v[174:175]
	v_lshl_add_u64 v[130:131], v[172:173], 0, v[202:203]
	global_load_dwordx4 v[192:195], v[130:131], off
	global_load_dwordx4 v[196:199], v[130:131], off offset:256
	v_or_b32_e32 v130, 16, v174
	v_or_b32_e32 v132, 32, v174
	v_or_b32_e32 v134, 48, v174
	v_ashrrev_i32_e32 v131, 31, v130
	v_ashrrev_i32_e32 v133, 31, v132
	v_ashrrev_i32_e32 v135, 31, v134
	v_lshlrev_b64 v[180:181], 11, v[130:131]
	v_lshlrev_b64 v[178:179], 11, v[132:133]
	v_lshlrev_b64 v[176:177], 11, v[134:135]
	v_lshl_add_u64 v[130:131], v[172:173], 0, v[180:181]
	v_lshl_add_u64 v[132:133], v[172:173], 0, v[178:179]
	v_lshl_add_u64 v[204:205], v[172:173], 0, v[176:177]
	v_add_co_u32_e32 v250, vcc, 0x38000, v130
	s_nop 1
	v_addc_co_u32_e32 v251, vcc, 0, v131, vcc
	global_load_dwordx4 v[246:249], v[250:251], off
	global_load_dwordx4 v[246:249], v[250:251], off offset:256
	v_add_co_u32_e32 v250, vcc, 0x40000, v130
	s_nop 1
	v_addc_co_u32_e32 v251, vcc, 0, v131, vcc
	global_load_dwordx4 v[246:249], v[250:251], off
	global_load_dwordx4 v[246:249], v[250:251], off offset:256
	v_add_co_u32_e32 v250, vcc, 0x40000, v132
	s_nop 1
	v_addc_co_u32_e32 v251, vcc, 0, v133, vcc
	global_load_dwordx4 v[246:249], v[250:251], off
	global_load_dwordx4 v[246:249], v[250:251], off offset:256
	v_add_co_u32_e32 v250, vcc, 0x40000, v204
	s_nop 1
	v_addc_co_u32_e32 v251, vcc, 0, v205, vcc
	global_load_dwordx4 v[246:249], v[250:251], off
	global_load_dwordx4 v[246:249], v[250:251], off offset:256
	global_load_dwordx4 v[150:153], v[130:131], off
	global_load_dwordx4 v[146:149], v[130:131], off offset:256
	global_load_dwordx4 v[142:145], v[132:133], off
	global_load_dwordx4 v[138:141], v[132:133], off offset:256
	global_load_dwordx4 v[134:137], v[204:205], off
	s_nop 0
	global_load_dwordx4 v[130:133], v[204:205], off offset:256
	v_and_b32_e32 v204, 64, v190
	v_xor_b32_e32 v191, 16, v190
	v_add_u32_e32 v204, 64, v204
	v_xor_b32_e32 v205, 32, v190
	v_cmp_lt_i32_e32 vcc, v191, v204
	v_lshl_add_u64 v[202:203], s[78:79], 0, v[202:203]
	v_lshl_add_u64 v[200:201], v[202:203], 0, v[200:201]
	v_cndmask_b32_e32 v191, v190, v191, vcc
	v_cmp_lt_i32_e32 vcc, v205, v204
	v_lshlrev_b32_e32 v191, 2, v191
	s_waitcnt vmcnt(0)
	v_lshlrev_b32_e32 v204, 16, v194
	v_cndmask_b32_e32 v210, v190, v205, vcc
	v_and_b32_e32 v205, 0xffff0000, v194
	v_lshlrev_b32_e32 v194, 16, v195
	v_and_b32_e32 v195, 0xffff0000, v195
	v_lshlrev_b32_e32 v202, 16, v192
	v_and_b32_e32 v203, 0xffff0000, v192
	v_lshlrev_b32_e32 v192, 16, v193
	v_and_b32_e32 v193, 0xffff0000, v193
	v_lshlrev_b32_e32 v206, 16, v196
	v_and_b32_e32 v207, 0xffff0000, v196
	v_lshlrev_b32_e32 v196, 16, v197
	v_and_b32_e32 v197, 0xffff0000, v197
	v_lshlrev_b32_e32 v208, 16, v198
	v_and_b32_e32 v209, 0xffff0000, v198
	v_lshlrev_b32_e32 v198, 16, v199
	v_and_b32_e32 v199, 0xffff0000, v199
	v_pk_add_f32 v[124:125], v[124:125], v[194:195]
	v_pk_add_f32 v[122:123], v[122:123], v[204:205]
	v_pk_add_f32 v[126:127], v[126:127], v[202:203]
	v_pk_add_f32 v[128:129], v[128:129], v[192:193]
	v_pk_add_f32 v[120:121], v[120:121], v[196:197]
	v_pk_add_f32 v[194:195], v[116:117], v[198:199]
	v_pk_mul_f32 v[116:117], v[122:123], v[122:123]
	v_pk_mul_f32 v[196:197], v[124:125], v[124:125]
	v_pk_add_f32 v[118:119], v[118:119], v[206:207]
	v_pk_add_f32 v[192:193], v[114:115], v[208:209]
	v_cvt_pk_bf16_f32 v114, v126, v127
	v_cvt_pk_bf16_f32 v115, v128, v129
	v_pk_fma_f32 v[128:129], v[128:129], v[128:129], v[196:197]
	v_pk_fma_f32 v[116:117], v[126:127], v[126:127], v[116:117]
	v_pk_fma_f32 v[126:127], v[120:121], v[120:121], v[128:129]
	v_pk_fma_f32 v[116:117], v[118:119], v[118:119], v[116:117]
	v_pk_fma_f32 v[126:127], v[194:195], v[194:195], v[126:127]
	v_pk_fma_f32 v[116:117], v[192:193], v[192:193], v[116:117]
	s_nop 0
	v_add_f32_e32 v116, v116, v117
	v_add_f32_e32 v117, v126, v127
	v_add_f32_e32 v126, v116, v117
	ds_bpermute_b32 v127, v191, v126
	v_cvt_pk_bf16_f32 v116, v122, v123
	v_cvt_pk_bf16_f32 v117, v124, v125
	global_store_dwordx4 v[200:201], v[114:117], off
	v_cvt_pk_bf16_f32 v118, v118, v119
	v_cvt_pk_bf16_f32 v119, v120, v121
	v_cvt_pk_bf16_f32 v120, v192, v193
	v_cvt_pk_bf16_f32 v121, v194, v195
	global_store_dwordx4 v[200:201], v[118:121], off offset:256
	s_waitcnt lgkmcnt(0)
	v_add_f32_e32 v115, v126, v127
	v_lshlrev_b32_e32 v114, 2, v210
	ds_bpermute_b32 v116, v114, v115
	s_and_saveexec_b64 s[2:3], s[4:5]
	s_cbranch_execz .LBB0_925
	s_waitcnt lgkmcnt(0)
	v_add_f32_e32 v115, v115, v116
	ds_write_b32 v185, v115

.LBB0_1629:
	s_lshl_b32 s11, s36, 8
	v_lshl_or_b32 v170, s10, 8, v183
	v_add_u32_e32 v174, s11, v1
	v_ashrrev_i32_e32 v171, 31, v170
	v_lshlrev_b64 v[200:201], 1, v[170:171]
	v_ashrrev_i32_e32 v175, 31, v174
	v_lshl_add_u64 v[172:173], s[78:79], 0, v[200:201]
	v_lshlrev_b64 v[202:203], 11, v[174:175]
	v_lshl_add_u64 v[130:131], v[172:173], 0, v[202:203]
	global_load_dwordx4 v[192:195], v[130:131], off
	global_load_dwordx4 v[196:199], v[130:131], off offset:256
	v_or_b32_e32 v130, 16, v174
	v_or_b32_e32 v132, 32, v174
	v_or_b32_e32 v134, 48, v174
	v_ashrrev_i32_e32 v131, 31, v130
	v_ashrrev_i32_e32 v133, 31, v132
	v_ashrrev_i32_e32 v135, 31, v134
	v_lshlrev_b64 v[180:181], 11, v[130:131]
	v_lshlrev_b64 v[178:179], 11, v[132:133]
	v_lshlrev_b64 v[176:177], 11, v[134:135]
	v_lshl_add_u64 v[130:131], v[172:173], 0, v[180:181]
	v_lshl_add_u64 v[132:133], v[172:173], 0, v[178:179]
	v_lshl_add_u64 v[190:191], v[172:173], 0, v[176:177]
	v_add_co_u32_e32 v250, vcc, 0x38000, v130
	s_nop 1
	v_addc_co_u32_e32 v251, vcc, 0, v131, vcc
	global_load_dwordx4 v[246:249], v[250:251], off
	global_load_dwordx4 v[246:249], v[250:251], off offset:256
	v_add_co_u32_e32 v250, vcc, 0x40000, v130
	s_nop 1
	v_addc_co_u32_e32 v251, vcc, 0, v131, vcc
	global_load_dwordx4 v[246:249], v[250:251], off
	global_load_dwordx4 v[246:249], v[250:251], off offset:256
	v_add_co_u32_e32 v250, vcc, 0x40000, v132
	s_nop 1
	v_addc_co_u32_e32 v251, vcc, 0, v133, vcc
	global_load_dwordx4 v[246:249], v[250:251], off
	global_load_dwordx4 v[246:249], v[250:251], off offset:256
	v_add_co_u32_e32 v250, vcc, 0x40000, v190
	s_nop 1
	v_addc_co_u32_e32 v251, vcc, 0, v191, vcc
	global_load_dwordx4 v[246:249], v[250:251], off
	global_load_dwordx4 v[246:249], v[250:251], off offset:256
	global_load_dwordx4 v[150:153], v[130:131], off
	global_load_dwordx4 v[146:149], v[130:131], off offset:256
	global_load_dwordx4 v[142:145], v[132:133], off
	global_load_dwordx4 v[138:141], v[132:133], off offset:256
	global_load_dwordx4 v[134:137], v[190:191], off
	s_nop 0
	global_load_dwordx4 v[130:133], v[190:191], off offset:256
	v_and_b32_e32 v191, 64, v189
	v_xor_b32_e32 v190, 16, v189
	v_add_u32_e32 v191, 64, v191
	v_xor_b32_e32 v204, 32, v189
	v_cmp_lt_i32_e32 vcc, v190, v191
	v_lshl_add_u64 v[202:203], s[78:79], 0, v[202:203]
	v_lshl_add_u64 v[200:201], v[202:203], 0, v[200:201]
	v_cndmask_b32_e32 v190, v189, v190, vcc
	v_cmp_lt_i32_e32 vcc, v204, v191
	v_lshlrev_b32_e32 v190, 2, v190
	s_waitcnt vmcnt(0)
	v_and_b32_e32 v205, 0xffff0000, v194
	v_cndmask_b32_e32 v191, v189, v204, vcc
	v_lshlrev_b32_e32 v204, 16, v194
	v_lshlrev_b32_e32 v194, 16, v195
	v_and_b32_e32 v195, 0xffff0000, v195
	v_lshlrev_b32_e32 v202, 16, v192
	v_and_b32_e32 v203, 0xffff0000, v192
	v_lshlrev_b32_e32 v192, 16, v193
	v_and_b32_e32 v193, 0xffff0000, v193
	v_lshlrev_b32_e32 v206, 16, v196
	v_and_b32_e32 v207, 0xffff0000, v196
	v_lshlrev_b32_e32 v196, 16, v197
	v_and_b32_e32 v197, 0xffff0000, v197
	v_lshlrev_b32_e32 v208, 16, v198
	v_and_b32_e32 v209, 0xffff0000, v198
	v_lshlrev_b32_e32 v198, 16, v199
	v_and_b32_e32 v199, 0xffff0000, v199
	v_pk_add_f32 v[124:125], v[124:125], v[194:195]
	v_pk_add_f32 v[122:123], v[122:123], v[204:205]
	v_pk_add_f32 v[126:127], v[126:127], v[202:203]
	v_pk_add_f32 v[128:129], v[128:129], v[192:193]
	v_pk_add_f32 v[120:121], v[120:121], v[196:197]
	v_pk_add_f32 v[194:195], v[116:117], v[198:199]
	v_pk_mul_f32 v[116:117], v[122:123], v[122:123]
	v_pk_mul_f32 v[196:197], v[124:125], v[124:125]
	v_pk_add_f32 v[118:119], v[118:119], v[206:207]
	v_pk_add_f32 v[192:193], v[114:115], v[208:209]
	v_cvt_pk_bf16_f32 v114, v126, v127
	v_cvt_pk_bf16_f32 v115, v128, v129
	v_pk_fma_f32 v[128:129], v[128:129], v[128:129], v[196:197]
	v_pk_fma_f32 v[116:117], v[126:127], v[126:127], v[116:117]
	v_pk_fma_f32 v[126:127], v[120:121], v[120:121], v[128:129]
	v_pk_fma_f32 v[116:117], v[118:119], v[118:119], v[116:117]
	v_pk_fma_f32 v[126:127], v[194:195], v[194:195], v[126:127]
	v_pk_fma_f32 v[116:117], v[192:193], v[192:193], v[116:117]
	s_nop 0
	v_add_f32_e32 v116, v116, v117
	v_add_f32_e32 v117, v126, v127
	v_add_f32_e32 v126, v116, v117
	ds_bpermute_b32 v127, v190, v126
	v_cvt_pk_bf16_f32 v116, v122, v123
	v_cvt_pk_bf16_f32 v117, v124, v125
	global_store_dwordx4 v[200:201], v[114:117], off
	v_cvt_pk_bf16_f32 v118, v118, v119
	v_cvt_pk_bf16_f32 v119, v120, v121
	v_cvt_pk_bf16_f32 v120, v192, v193
	v_cvt_pk_bf16_f32 v121, v194, v195
	global_store_dwordx4 v[200:201], v[118:121], off offset:256
	s_waitcnt lgkmcnt(0)
	v_add_f32_e32 v115, v126, v127
	v_lshlrev_b32_e32 v114, 2, v191
	ds_bpermute_b32 v116, v114, v115
	s_and_saveexec_b64 s[2:3], s[4:5]
	s_cbranch_execz .LBB0_1631
	s_waitcnt lgkmcnt(0)
	v_add_f32_e32 v115, v115, v116
	ds_write_b32 v184, v115

.LBB0_1844:
	s_lshl_b32 s13, s13, 8
	v_lshl_or_b32 v170, s12, 8, v183
	v_add_u32_e32 v174, s13, v1
	v_ashrrev_i32_e32 v171, 31, v170
	v_lshlrev_b64 v[200:201], 1, v[170:171]
	v_ashrrev_i32_e32 v175, 31, v174
	v_lshl_add_u64 v[172:173], s[78:79], 0, v[200:201]
	v_lshlrev_b64 v[202:203], 11, v[174:175]
	v_lshl_add_u64 v[130:131], v[172:173], 0, v[202:203]
	global_load_dwordx4 v[192:195], v[130:131], off
	global_load_dwordx4 v[196:199], v[130:131], off offset:256
	v_or_b32_e32 v130, 16, v174
	v_or_b32_e32 v132, 32, v174
	v_or_b32_e32 v134, 48, v174
	v_ashrrev_i32_e32 v131, 31, v130
	v_ashrrev_i32_e32 v133, 31, v132
	v_ashrrev_i32_e32 v135, 31, v134
	v_lshlrev_b64 v[180:181], 11, v[130:131]
	v_lshlrev_b64 v[178:179], 11, v[132:133]
	v_lshlrev_b64 v[176:177], 11, v[134:135]
	v_lshl_add_u64 v[130:131], v[172:173], 0, v[180:181]
	v_lshl_add_u64 v[132:133], v[172:173], 0, v[178:179]
	v_lshl_add_u64 v[190:191], v[172:173], 0, v[176:177]
	v_add_co_u32_e32 v250, vcc, 0x38000, v130
	s_nop 1
	v_addc_co_u32_e32 v251, vcc, 0, v131, vcc
	global_load_dwordx4 v[246:249], v[250:251], off
	global_load_dwordx4 v[246:249], v[250:251], off offset:256
	v_add_co_u32_e32 v250, vcc, 0x40000, v130
	s_nop 1
	v_addc_co_u32_e32 v251, vcc, 0, v131, vcc
	global_load_dwordx4 v[246:249], v[250:251], off
	global_load_dwordx4 v[246:249], v[250:251], off offset:256
	v_add_co_u32_e32 v250, vcc, 0x40000, v132
	s_nop 1
	v_addc_co_u32_e32 v251, vcc, 0, v133, vcc
	global_load_dwordx4 v[246:249], v[250:251], off
	global_load_dwordx4 v[246:249], v[250:251], off offset:256
	v_add_co_u32_e32 v250, vcc, 0x40000, v190
	s_nop 1
	v_addc_co_u32_e32 v251, vcc, 0, v191, vcc
	global_load_dwordx4 v[246:249], v[250:251], off
	global_load_dwordx4 v[246:249], v[250:251], off offset:256
	global_load_dwordx4 v[150:153], v[130:131], off
	global_load_dwordx4 v[146:149], v[130:131], off offset:256
	global_load_dwordx4 v[142:145], v[132:133], off
	global_load_dwordx4 v[138:141], v[132:133], off offset:256
	global_load_dwordx4 v[134:137], v[190:191], off
	s_nop 0
	global_load_dwordx4 v[130:133], v[190:191], off offset:256
	v_and_b32_e32 v191, 64, v189
	v_xor_b32_e32 v190, 16, v189
	v_add_u32_e32 v191, 64, v191
	v_xor_b32_e32 v204, 32, v189
	v_cmp_lt_i32_e32 vcc, v190, v191
	v_lshl_add_u64 v[202:203], s[78:79], 0, v[202:203]
	v_lshl_add_u64 v[200:201], v[202:203], 0, v[200:201]
	v_cndmask_b32_e32 v190, v189, v190, vcc
	v_cmp_lt_i32_e32 vcc, v204, v191
	v_lshlrev_b32_e32 v190, 2, v190
	s_waitcnt vmcnt(0)
	v_and_b32_e32 v205, 0xffff0000, v194
	v_cndmask_b32_e32 v191, v189, v204, vcc
	v_lshlrev_b32_e32 v204, 16, v194
	v_lshlrev_b32_e32 v194, 16, v195
	v_and_b32_e32 v195, 0xffff0000, v195
	v_lshlrev_b32_e32 v202, 16, v192
	v_and_b32_e32 v203, 0xffff0000, v192
	v_lshlrev_b32_e32 v192, 16, v193
	v_and_b32_e32 v193, 0xffff0000, v193
	v_lshlrev_b32_e32 v206, 16, v196
	v_and_b32_e32 v207, 0xffff0000, v196
	v_lshlrev_b32_e32 v196, 16, v197
	v_and_b32_e32 v197, 0xffff0000, v197
	v_lshlrev_b32_e32 v208, 16, v198
	v_and_b32_e32 v209, 0xffff0000, v198
	v_lshlrev_b32_e32 v198, 16, v199
	v_and_b32_e32 v199, 0xffff0000, v199
	v_pk_add_f32 v[124:125], v[124:125], v[194:195]
	v_pk_add_f32 v[122:123], v[122:123], v[204:205]
	v_pk_add_f32 v[126:127], v[126:127], v[202:203]
	v_pk_add_f32 v[128:129], v[128:129], v[192:193]
	v_pk_add_f32 v[120:121], v[120:121], v[196:197]
	v_pk_add_f32 v[194:195], v[116:117], v[198:199]
	v_pk_mul_f32 v[116:117], v[122:123], v[122:123]
	v_pk_mul_f32 v[196:197], v[124:125], v[124:125]
	v_pk_add_f32 v[118:119], v[118:119], v[206:207]
	v_pk_add_f32 v[192:193], v[114:115], v[208:209]
	v_cvt_pk_bf16_f32 v114, v126, v127
	v_cvt_pk_bf16_f32 v115, v128, v129
	v_pk_fma_f32 v[128:129], v[128:129], v[128:129], v[196:197]
	v_pk_fma_f32 v[116:117], v[126:127], v[126:127], v[116:117]
	v_pk_fma_f32 v[126:127], v[120:121], v[120:121], v[128:129]
	v_pk_fma_f32 v[116:117], v[118:119], v[118:119], v[116:117]
	v_pk_fma_f32 v[126:127], v[194:195], v[194:195], v[126:127]
	v_pk_fma_f32 v[116:117], v[192:193], v[192:193], v[116:117]
	s_nop 0
	v_add_f32_e32 v116, v116, v117
	v_add_f32_e32 v117, v126, v127
	v_add_f32_e32 v126, v116, v117
	ds_bpermute_b32 v127, v190, v126
	v_cvt_pk_bf16_f32 v116, v122, v123
	v_cvt_pk_bf16_f32 v117, v124, v125
	global_store_dwordx4 v[200:201], v[114:117], off
	v_cvt_pk_bf16_f32 v118, v118, v119
	v_cvt_pk_bf16_f32 v119, v120, v121
	v_cvt_pk_bf16_f32 v120, v192, v193
	v_cvt_pk_bf16_f32 v121, v194, v195
	global_store_dwordx4 v[200:201], v[118:121], off offset:256
	s_waitcnt lgkmcnt(0)
	v_add_f32_e32 v115, v126, v127
	v_lshlrev_b32_e32 v114, 2, v191
	ds_bpermute_b32 v116, v114, v115
	s_and_saveexec_b64 s[2:3], s[4:5]
	s_cbranch_execz .LBB0_1846
	s_waitcnt lgkmcnt(0)
	v_add_f32_e32 v115, v115, v116
	ds_write_b32 v184, v115
